# no-permlane P/V key order + MLA loops: row-sum lane-pair exchange once per unit, LDS-DMA source addresses in scalar-base + 32-bit offset form (no 64-bit VALU adds per step)
# baseline (speedup 1.0000x reference)
.LBB0_891:
	s_lshr_b32 s16, s19, 6
	s_and_b64 s[12:13], s[12:13], exec
	s_cselect_b32 s12, s19, s16
	s_and_b32 s17, s12, 7
	s_mul_i32 s12, s9, 0xc00
	s_mul_hi_u32 s13, s8, 0xc00
	s_add_i32 s13, s13, s12
	s_mul_i32 s12, s8, 0xc00
	v_readlane_b32 s20, v242, 21
	v_readlane_b32 s21, v242, 22
	s_add_u32 s12, s20, s12
	s_addc_u32 s13, s21, s13
	s_mul_i32 s16, s17, 0x180
	s_add_u32 s28, s12, s16
	s_addc_u32 s29, s13, 0
	s_mul_i32 s12, s1, 0xc00
	s_mul_hi_u32 s13, s0, 0xc00
	s_add_i32 s13, s13, s12
	s_mul_i32 s12, s0, 0xc00
	s_add_u32 s12, s27, s12
	s_addc_u32 s13, s30, s13
	s_add_u32 s12, s12, s16
	s_mul_i32 s20, s15, 0x3000000
	s_mul_hi_u32 s21, s14, 0x3000000
	s_addc_u32 s13, s13, 0
	s_add_i32 s21, s21, s20
	s_mul_i32 s20, s14, 0x3000000
	s_add_u32 s20, s27, s20
	s_addc_u32 s21, s30, s21
	s_add_u32 s22, s20, s16
	s_addc_u32 s23, s21, 0
	s_lshl_b64 s[0:1], s[0:1], 12
	s_add_u32 s0, s31, s0
	s_addc_u32 s1, s34, s1
	s_lshl_b32 s16, s17, 9
	s_add_u32 s0, s0, s16
	s_addc_u32 s1, s1, 0
	s_add_u32 s24, s0, 0x100
	s_addc_u32 s25, s1, 0
	s_lshl_b64 s[14:15], s[14:15], 26
	s_add_u32 s14, s31, s14
	s_addc_u32 s15, s34, s15
	s_add_u32 s14, s14, s16
	s_addc_u32 s15, s15, 0
	s_add_u32 s33, s14, 0x100
	v_readfirstlane_b32 s68, v0
	s_addc_u32 s35, s15, 0
	s_lshr_b32 s20, s68, 6
	s_lshl_b32 s16, s20, 5
	v_or_b32_e32 v4, s16, v1
	v_mov_b64_e32 v[2:3], s[28:29]
	s_movk_i32 s14, 0xc00
	v_mad_u64_u32 v[2:3], s[14:15], v4, s14, v[2:3]
	s_andn2_b32 s68, s68, 63
	v_lshl_add_u64 v[2:3], v[2:3], 0, v[148:149]
	global_load_dwordx4 v[142:145], v[2:3], off
	global_load_dwordx4 v[138:141], v[2:3], off offset:32
	global_load_dwordx4 v[134:137], v[2:3], off offset:64
	global_load_dwordx4 v[130:133], v[2:3], off offset:96
	global_load_dwordx4 v[126:129], v[2:3], off offset:128
	global_load_dwordx4 v[122:125], v[2:3], off offset:160
	global_load_dwordx4 v[118:121], v[2:3], off offset:192
	global_load_dwordx4 v[114:117], v[2:3], off offset:224
	global_load_dwordx4 v[110:113], v[2:3], off offset:256
	global_load_dwordx4 v[106:109], v[2:3], off offset:288
	global_load_dwordx4 v[102:105], v[2:3], off offset:320
	global_load_dwordx4 v[98:101], v[2:3], off offset:352
	v_or_b32_e32 v2, s68, v166
	v_mul_hi_i32 v3, v2, s11
	v_lshrrev_b32_e32 v4, 31, v3
	v_ashrrev_i32_e32 v3, 2, v3
	v_add_u32_e32 v3, v3, v4
	v_mul_lo_u32 v4, v3, 24
	v_sub_u32_e32 v4, v2, v4
	v_mul_lo_u32 v5, v3, s18
	v_lshrrev_b32_e32 v3, 1, v3
	v_bitop3_b32 v3, v3, v4, 7 bitop3:0x6c
	v_lshl_add_u32 v160, v3, 3, v5
	v_add_u32_e32 v3, 0x200, v2
	v_mul_hi_i32 v4, v3, s11
	v_lshrrev_b32_e32 v5, 31, v4
	v_ashrrev_i32_e32 v4, 2, v4
	v_add_u32_e32 v4, v4, v5
	v_mul_lo_u32 v5, v4, 24
	v_sub_u32_e32 v3, v3, v5
	v_mul_lo_u32 v5, v4, s18
	v_lshrrev_b32_e32 v4, 1, v4
	v_bitop3_b32 v3, v4, v3, 7 bitop3:0x6c
	v_lshl_add_u32 v162, v3, 3, v5
	v_add_u32_e32 v3, 0x400, v2
	v_mul_hi_i32 v4, v3, s11
	v_lshrrev_b32_e32 v5, 31, v4
	v_ashrrev_i32_e32 v4, 2, v4
	v_add_u32_e32 v4, v4, v5
	s_ashr_i32 s14, s68, 4
	v_mul_lo_u32 v5, v4, 24
	s_and_b32 s15, s14, 0x1ffff0
	s_lshr_b32 s14, s14, 1
	v_sub_u32_e32 v3, v3, v5
	v_mul_lo_u32 v5, v4, s18
	v_lshrrev_b32_e32 v4, 1, v4
	s_and_b32 s14, s14, 4
	v_bitop3_b32 v3, v4, v3, 7 bitop3:0x6c
	s_or_b32 s14, s15, s14
	v_lshl_add_u32 v170, v3, 3, v5
	v_or_b32_e32 v3, s14, v169
	v_lshrrev_b32_e32 v173, 1, v3
	v_xor_b32_e32 v173, v173, v3
	v_and_b32_e32 v173, 4, v173
	v_lshl_or_b32 v173, v173, 1, v173
	v_xor_b32_e32 v3, v3, v173
	s_add_i32 s14, s68, 0x200
	s_ashr_i32 s14, s14, 4
	s_and_b32 s15, s14, 0x1ffff0
	s_lshr_b32 s14, s14, 1
	s_and_b32 s14, s14, 4
	v_and_or_b32 v2, v2, s10, v165
	s_or_b32 s14, s15, s14
	v_lshl_or_b32 v172, v3, 11, v2
	v_or_b32_e32 v3, s14, v169
	v_lshrrev_b32_e32 v175, 1, v3
	v_xor_b32_e32 v175, v175, v3
	v_and_b32_e32 v175, 4, v175
	v_lshl_or_b32 v175, v175, 1, v175
	v_xor_b32_e32 v3, v3, v175
	s_lshl_b32 s14, s20, 10
	s_add_i32 s69, s14, 0
	v_ashrrev_i32_e32 v161, 31, v160
	v_lshl_or_b32 v174, v3, 11, v2
	s_add_i32 m0, s69, 0x8000
	v_lshl_add_u64 v[2:3], v[160:161], 1, s[12:13]
	v_ashrrev_i32_e32 v163, 31, v162
	global_load_lds_dwordx4 v[2:3], off
	v_lshl_add_u64 v[2:3], v[162:163], 1, s[12:13]
	s_add_i32 m0, s69, 0xa000
	v_ashrrev_i32_e32 v171, 31, v170
	global_load_lds_dwordx4 v[2:3], off
	v_lshl_add_u64 v[2:3], v[170:171], 1, s[12:13]
	s_add_i32 m0, s69, 0xc000
	v_ashrrev_i32_e32 v173, 31, v172
	global_load_lds_dwordx4 v[2:3], off
	v_lshl_add_u64 v[2:3], v[172:173], 1, s[0:1]
	v_lshl_add_u64 v[2:3], v[2:3], 0, s[6:7]
	s_mov_b32 m0, s69
	v_ashrrev_i32_e32 v175, 31, v174
	global_load_lds_dwordx4 v[2:3], off
	v_lshl_add_u64 v[2:3], v[174:175], 1, s[0:1]
	v_lshl_add_u64 v[2:3], v[2:3], 0, s[6:7]
	s_add_i32 m0, s69, 0x2000
	v_mov_b32_e32 v151, 0
	global_load_lds_dwordx4 v[2:3], off
	s_waitcnt vmcnt(0)
	s_add_i32 s0, s4, 1
	s_mov_b32 s4, 0
	s_mov_b64 s[14:15], 64
	v_mov_b32_e32 v2, 0
	v_mov_b32_e32 v3, v151
	v_mov_b32_e32 v4, v151
	v_mov_b32_e32 v5, v151
	v_mov_b32_e32 v6, v151
	v_mov_b32_e32 v7, v151
	v_mov_b32_e32 v8, v151
	v_mov_b32_e32 v9, v151
	v_mov_b32_e32 v10, v151
	v_mov_b32_e32 v11, v151
	v_mov_b32_e32 v12, v151
	v_mov_b32_e32 v13, v151
	v_mov_b32_e32 v14, v151
	v_mov_b32_e32 v15, v151
	v_mov_b32_e32 v16, v151
	v_mov_b32_e32 v17, v151
	v_mov_b32_e32 v18, 0
	v_mov_b32_e32 v19, v151
	v_mov_b32_e32 v20, v151
	v_mov_b32_e32 v21, v151
	v_mov_b32_e32 v22, v151
	v_mov_b32_e32 v23, v151
	v_mov_b32_e32 v24, v151
	v_mov_b32_e32 v25, v151
	v_mov_b32_e32 v26, v151
	v_mov_b32_e32 v27, v151
	v_mov_b32_e32 v28, v151
	v_mov_b32_e32 v29, v151
	v_mov_b32_e32 v30, v151
	v_mov_b32_e32 v31, v151
	v_mov_b32_e32 v32, v151
	v_mov_b32_e32 v33, v151
	v_mov_b32_e32 v34, 0
	v_mov_b32_e32 v35, v151
	v_mov_b32_e32 v36, v151
	v_mov_b32_e32 v37, v151
	v_mov_b32_e32 v38, v151
	v_mov_b32_e32 v39, v151
	v_mov_b32_e32 v40, v151
	v_mov_b32_e32 v41, v151
	v_mov_b32_e32 v42, v151
	v_mov_b32_e32 v43, v151
	v_mov_b32_e32 v44, v151
	v_mov_b32_e32 v45, v151
	v_mov_b32_e32 v46, v151
	v_mov_b32_e32 v47, v151
	v_mov_b32_e32 v48, v151
	v_mov_b32_e32 v49, v151
	v_mov_b32_e32 v50, 0
	v_mov_b32_e32 v51, v151
	v_mov_b32_e32 v52, v151
	v_mov_b32_e32 v53, v151
	v_mov_b32_e32 v54, v151
	v_mov_b32_e32 v55, v151
	v_mov_b32_e32 v56, v151
	v_mov_b32_e32 v57, v151
	v_mov_b32_e32 v58, v151
	v_mov_b32_e32 v59, v151
	v_mov_b32_e32 v60, v151
	v_mov_b32_e32 v61, v151
	v_mov_b32_e32 v62, v151
	v_mov_b32_e32 v63, v151
	v_mov_b32_e32 v64, v151
	v_mov_b32_e32 v65, v151
	s_waitcnt vmcnt(0) lgkmcnt(0)
	s_barrier
	v_lshlrev_b32_e32 v222, 1, v160
	v_lshlrev_b32_e32 v223, 1, v162
	v_lshlrev_b32_e32 v224, 1, v170
	v_lshlrev_b32_e32 v225, 1, v172
	v_lshlrev_b32_e32 v226, 1, v174
.LBB0_892:
	v_sub_co_u32_e64 v66, s[28:29], s4, 3
	s_and_b32 s21, s4, 1
	s_add_i32 s1, s4, 1
	v_readfirstlane_b32 s4, v66
	s_lshl_b64 s[36:37], s[4:5], 6
	s_and_b64 s[38:39], s[28:29], exec
	s_cselect_b32 s37, s15, s37
	s_cselect_b32 s36, s14, s36
	s_mul_i32 s39, s37, 0xc00
	s_mul_hi_u32 s40, s36, 0xc00
	s_cselect_b32 s4, s13, s23
	s_cselect_b32 s38, s12, s22
	s_add_i32 s40, s40, s39
	s_mul_i32 s39, s36, 0xc00
	s_add_u32 s38, s38, s39
	s_addc_u32 s39, s4, s40
	s_xor_b32 s4, s21, 1
	s_mulk_i32 s4, 0x6000
	s_add_i32 s4, s69, s4
	s_add_i32 m0, s4, 0x8000
	s_nop 0
	global_load_lds_dwordx4 v222, s[38:39]
	s_add_i32 m0, s4, 0xa000
	s_lshl_b64 s[36:37], s[36:37], 12
	global_load_lds_dwordx4 v223, s[38:39]
	s_add_i32 m0, s4, 0xc000
	s_and_b64 s[28:29], s[28:29], exec
	s_cselect_b32 s28, s24, s33
	s_cselect_b32 s4, s25, s35
	s_add_u32 s28, s28, s36
	s_addc_u32 s29, s4, s37
	s_lshl_b32 s4, s21, 14
	s_xor_b32 s36, s4, 0x4000
	s_add_i32 s36, s69, s36
	global_load_lds_dwordx4 v224, s[38:39]
	s_mov_b32 m0, s36
	s_mulk_i32 s21, 0x6000
	global_load_lds_dwordx4 v225, s[28:29]
	s_add_i32 m0, s36, 0x2000
	s_nop 0
	global_load_lds_dwordx4 v226, s[28:29]
	v_add_u32_e32 v70, s21, v179
	v_add_u32_e32 v71, v70, v178
	ds_read_b128 v[66:69], v71 offset:32768
	v_add_u32_e32 v153, v70, v180
	v_add_u32_e32 v155, v70, v181
	v_add_u32_e32 v157, v70, v182
	v_add_u32_e32 v159, v70, v183
	v_add_u32_e32 v193, v70, v184
	v_add_u32_e32 v198, v70, v185
	v_add_u32_e32 v199, v70, v186
	v_add_u32_e32 v200, v70, v187
	s_waitcnt lgkmcnt(0)
	v_mfma_f32_32x32x16_bf16 v[82:97], v[66:69], v[142:145], 0
	ds_read_b128 v[66:69], v153 offset:32768
	v_add_u32_e32 v201, v70, v188
	v_add_u32_e32 v202, v70, v189
	v_add_u32_e32 v203, v70, v190
	s_waitcnt lgkmcnt(0)
	v_mfma_f32_32x32x16_bf16 v[82:97], v[66:69], v[138:141], v[82:97]
	ds_read_b128 v[66:69], v155 offset:32768
	s_waitcnt lgkmcnt(0)
	v_mfma_f32_32x32x16_bf16 v[82:97], v[66:69], v[134:137], v[82:97]
	ds_read_b128 v[66:69], v157 offset:32768
	s_waitcnt lgkmcnt(0)
	v_mfma_f32_32x32x16_bf16 v[82:97], v[66:69], v[130:133], v[82:97]
	ds_read_b128 v[66:69], v159 offset:32768
	s_waitcnt lgkmcnt(0)
	v_mfma_f32_32x32x16_bf16 v[82:97], v[66:69], v[126:129], v[82:97]
	ds_read_b128 v[66:69], v193 offset:32768
	s_waitcnt lgkmcnt(0)
	v_mfma_f32_32x32x16_bf16 v[82:97], v[66:69], v[122:125], v[82:97]
	ds_read_b128 v[66:69], v198 offset:32768
	s_waitcnt lgkmcnt(0)
	v_mfma_f32_32x32x16_bf16 v[82:97], v[66:69], v[118:121], v[82:97]
	ds_read_b128 v[66:69], v199 offset:32768
	s_waitcnt lgkmcnt(0)
	v_mfma_f32_32x32x16_bf16 v[82:97], v[66:69], v[114:117], v[82:97]
	ds_read_b128 v[66:69], v200 offset:32768
	s_waitcnt lgkmcnt(0)
	v_mfma_f32_32x32x16_bf16 v[82:97], v[66:69], v[110:113], v[82:97]
	ds_read_b128 v[66:69], v201 offset:32768
	s_waitcnt lgkmcnt(0)
	v_mfma_f32_32x32x16_bf16 v[82:97], v[66:69], v[106:109], v[82:97]
	ds_read_b128 v[66:69], v202 offset:32768
	s_waitcnt lgkmcnt(0)
	v_mfma_f32_32x32x16_bf16 v[82:97], v[66:69], v[102:105], v[82:97]
	ds_read_b128 v[66:69], v203 offset:32768
	s_waitcnt lgkmcnt(0)
	v_mfma_f32_32x32x16_bf16 v[82:97], v[66:69], v[98:101], v[82:97]
	ds_read_b128 v[66:69], v71 offset:45056
	ds_read_b128 v[194:197], v153 offset:45056
	s_nop 9
	v_exp_f32_e32 v204, v88
	v_exp_f32_e32 v205, v89
	v_exp_f32_e32 v206, v90
	v_exp_f32_e32 v207, v91
	v_exp_f32_e32 v208, v92
	v_exp_f32_e32 v209, v93
	v_exp_f32_e32 v210, v94
	s_waitcnt lgkmcnt(0)
	v_mfma_f32_32x32x16_bf16 v[66:81], v[66:69], v[142:145], 0
	v_exp_f32_e32 v211, v95
	v_exp_f32_e32 v212, v96
	v_exp_f32_e32 v213, v97
	v_add_u32_e32 v153, s4, v176
	v_cvt_pk_bf16_f32 v88, v210, v211
	v_cvt_pk_bf16_f32 v89, v212, v213
	v_mfma_f32_32x32x16_bf16 v[66:81], v[194:197], v[138:141], v[66:81]
	ds_read_b128 v[194:197], v155 offset:45056
	v_exp_f32_e32 v155, v82
	s_waitcnt lgkmcnt(0)
	v_mfma_f32_32x32x16_bf16 v[66:81], v[194:197], v[134:137], v[66:81]
	ds_read_b128 v[194:197], v157 offset:45056
	v_exp_f32_e32 v157, v83
	s_nop 0
	v_cvt_pk_bf16_f32 v82, v155, v157
	s_waitcnt lgkmcnt(0)
	v_mfma_f32_32x32x16_bf16 v[66:81], v[194:197], v[130:133], v[66:81]
	ds_read_b128 v[194:197], v159 offset:45056
	v_exp_f32_e32 v159, v84
	s_waitcnt lgkmcnt(0)
	v_mfma_f32_32x32x16_bf16 v[66:81], v[194:197], v[126:129], v[66:81]
	ds_read_b128 v[194:197], v193 offset:45056
	v_exp_f32_e32 v193, v85
	v_cvt_pk_bf16_f32 v85, v204, v205
	v_cvt_pk_bf16_f32 v83, v159, v193
	s_nop 1
	s_waitcnt lgkmcnt(0)
	v_mfma_f32_32x32x16_bf16 v[66:81], v[194:197], v[122:125], v[66:81]
	ds_read_b128 v[194:197], v198 offset:45056
	s_waitcnt lgkmcnt(0)
	v_mfma_f32_32x32x16_bf16 v[66:81], v[194:197], v[118:121], v[66:81]
	ds_read_b128 v[194:197], v199 offset:45056
	s_waitcnt lgkmcnt(0)
	v_mfma_f32_32x32x16_bf16 v[66:81], v[194:197], v[114:117], v[66:81]
	ds_read_b128 v[194:197], v200 offset:45056
	s_waitcnt lgkmcnt(0)
	v_mfma_f32_32x32x16_bf16 v[66:81], v[194:197], v[110:113], v[66:81]
	ds_read_b128 v[194:197], v201 offset:45056
	s_waitcnt lgkmcnt(0)
	v_mfma_f32_32x32x16_bf16 v[66:81], v[194:197], v[106:109], v[66:81]
	ds_read_b128 v[194:197], v202 offset:45056
	v_exp_f32_e32 v202, v86
	v_cvt_pk_bf16_f32 v86, v206, v207
	s_nop 1
	s_waitcnt lgkmcnt(0)
	v_mfma_f32_32x32x16_bf16 v[66:81], v[194:197], v[102:105], v[66:81]
	ds_read_b128 v[194:197], v203 offset:45056
	v_exp_f32_e32 v203, v87
	v_cvt_pk_bf16_f32 v87, v208, v209
	s_nop 1
	v_cvt_pk_bf16_f32 v84, v202, v203
	s_nop 1
	s_waitcnt lgkmcnt(0)
	v_mfma_f32_32x32x16_bf16 v[66:81], v[194:197], v[98:101], v[66:81]
	ds_read_b64_tr_b16 v[90:91], v153 offset:0
	ds_read_b64_tr_b16 v[92:93], v153 offset:0x800
	ds_read_b64_tr_b16 v[94:95], v153 offset:0x1000
	ds_read_b64_tr_b16 v[96:97], v153 offset:0x1800
	ds_read_b64_tr_b16 v[194:195], v153 offset:0x200
	ds_read_b64_tr_b16 v[196:197], v153 offset:0xa00
	ds_read_b64_tr_b16 v[198:199], v153 offset:0x1200
	ds_read_b64_tr_b16 v[200:201], v153 offset:0x1a00
	s_waitcnt lgkmcnt(4)
	s_nop 0
	v_mfma_f32_32x32x16_bf16 v[2:17], v[82:85], v[90:93], v[2:17]
	s_nop 9
	v_exp_f32_e32 v214, v66
	v_exp_f32_e32 v215, v67
	v_exp_f32_e32 v216, v68
	v_exp_f32_e32 v217, v69
	v_mfma_f32_32x32x16_bf16 v[2:17], v[86:89], v[94:97], v[2:17]
	ds_read_b64_tr_b16 v[66:67], v153 offset:0x400
	ds_read_b64_tr_b16 v[68:69], v153 offset:0xc00
	ds_read_b64_tr_b16 v[90:91], v153 offset:0x1400
	ds_read_b64_tr_b16 v[92:93], v153 offset:0x1c00
	s_waitcnt lgkmcnt(4)
	v_mfma_f32_32x32x16_bf16 v[18:33], v[82:85], v[194:197], v[18:33]
	v_exp_f32_e32 v194, v70
	v_exp_f32_e32 v195, v71
	v_exp_f32_e32 v196, v72
	v_exp_f32_e32 v197, v73
	v_mfma_f32_32x32x16_bf16 v[18:33], v[86:89], v[198:201], v[18:33]
	ds_read_b64_tr_b16 v[70:71], v153 offset:0x600
	ds_read_b64_tr_b16 v[72:73], v153 offset:0xe00
	ds_read_b64_tr_b16 v[94:95], v153 offset:0x1600
	ds_read_b64_tr_b16 v[96:97], v153 offset:0x1e00
	s_waitcnt lgkmcnt(4)
	v_mfma_f32_32x32x16_bf16 v[34:49], v[82:85], v[66:69], v[34:49]
	v_exp_f32_e32 v198, v74
	v_exp_f32_e32 v199, v75
	v_exp_f32_e32 v200, v76
	v_exp_f32_e32 v201, v77
	v_mfma_f32_32x32x16_bf16 v[34:49], v[86:89], v[90:93], v[34:49]
	ds_read_b64_tr_b16 v[66:67], v153 offset:0x2000
	ds_read_b64_tr_b16 v[68:69], v153 offset:0x2800
	ds_read_b64_tr_b16 v[74:75], v153 offset:0x3000
	ds_read_b64_tr_b16 v[76:77], v153 offset:0x3800
	s_waitcnt lgkmcnt(4)
	v_mfma_f32_32x32x16_bf16 v[50:65], v[82:85], v[70:73], v[50:65]
	v_exp_f32_e32 v249, v78
	v_exp_f32_e32 v250, v79
	v_cvt_pk_bf16_f32 v72, v194, v195
	v_cvt_pk_bf16_f32 v73, v196, v197
	v_mfma_f32_32x32x16_bf16 v[50:65], v[86:89], v[94:97], v[50:65]
	v_exp_f32_e32 v251, v80
	v_exp_f32_e32 v248, v81
	v_cvt_pk_bf16_f32 v78, v198, v199
	v_cvt_pk_bf16_f32 v79, v200, v201
	v_cvt_pk_bf16_f32 v80, v249, v250
	v_cvt_pk_bf16_f32 v70, v214, v215
	v_cvt_pk_bf16_f32 v71, v216, v217
	v_cvt_pk_bf16_f32 v81, v251, v248
	s_nop 0
	ds_read_b64_tr_b16 v[82:83], v153 offset:0x2200
	ds_read_b64_tr_b16 v[84:85], v153 offset:0x2a00
	ds_read_b64_tr_b16 v[86:87], v153 offset:0x3200
	ds_read_b64_tr_b16 v[88:89], v153 offset:0x3a00
	s_waitcnt lgkmcnt(4)
	s_nop 0
	v_mfma_f32_32x32x16_bf16 v[2:17], v[70:73], v[66:69], v[2:17]
	v_add_f32_e32 v246, v155, v157
	v_add_f32_e32 v247, v214, v215
	v_add_f32_e32 v246, v246, v159
	v_add_f32_e32 v247, v247, v216
	v_mfma_f32_32x32x16_bf16 v[2:17], v[78:81], v[74:77], v[2:17]
	v_add_f32_e32 v246, v246, v193
	v_add_f32_e32 v247, v247, v217
	v_add_f32_e32 v246, v246, v202
	v_add_f32_e32 v247, v247, v194
	ds_read_b64_tr_b16 v[66:67], v153 offset:0x2400
	ds_read_b64_tr_b16 v[68:69], v153 offset:0x2c00
	ds_read_b64_tr_b16 v[74:75], v153 offset:0x3400
	ds_read_b64_tr_b16 v[76:77], v153 offset:0x3c00
	s_waitcnt lgkmcnt(4)
	v_mfma_f32_32x32x16_bf16 v[18:33], v[70:73], v[82:85], v[18:33]
	v_add_f32_e32 v246, v246, v203
	v_add_f32_e32 v247, v247, v195
	v_add_f32_e32 v246, v246, v204
	v_add_f32_e32 v247, v247, v196
	v_mfma_f32_32x32x16_bf16 v[18:33], v[78:81], v[86:89], v[18:33]
	v_add_f32_e32 v246, v246, v205
	v_add_f32_e32 v247, v247, v197
	v_add_f32_e32 v246, v246, v206
	v_add_f32_e32 v247, v247, v198
	ds_read_b64_tr_b16 v[82:83], v153 offset:0x2600
	ds_read_b64_tr_b16 v[84:85], v153 offset:0x2e00
	ds_read_b64_tr_b16 v[86:87], v153 offset:0x3600
	ds_read_b64_tr_b16 v[88:89], v153 offset:0x3e00
	s_waitcnt lgkmcnt(4)
	v_mfma_f32_32x32x16_bf16 v[34:49], v[70:73], v[66:69], v[34:49]
	v_add_f32_e32 v246, v246, v207
	v_add_f32_e32 v247, v247, v199
	v_add_f32_e32 v246, v246, v208
	v_add_f32_e32 v247, v247, v200
	v_mfma_f32_32x32x16_bf16 v[34:49], v[78:81], v[74:77], v[34:49]
	v_add_f32_e32 v246, v246, v209
	v_add_f32_e32 v247, v247, v201
	v_add_f32_e32 v246, v246, v210
	v_add_f32_e32 v247, v247, v249
	s_waitcnt lgkmcnt(0)
	v_mfma_f32_32x32x16_bf16 v[50:65], v[70:73], v[82:85], v[50:65]
	v_add_f32_e32 v246, v246, v211
	v_add_f32_e32 v247, v247, v250
	v_add_f32_e32 v246, v246, v212
	v_add_f32_e32 v247, v247, v251
	v_add_f32_e32 v246, v246, v213
	v_add_f32_e32 v247, v247, v248
	v_add_f32_e32 v246, v246, v247
	v_add_f32_e32 v151, v151, v246
	s_waitcnt vmcnt(0)
	s_add_u32 s14, s14, 64
	s_addc_u32 s15, s15, 0
	s_cmp_eq_u32 s0, s1
	s_mov_b32 s4, s1
	s_waitcnt vmcnt(0)
	s_barrier
	v_mfma_f32_32x32x16_bf16 v[50:65], v[78:81], v[86:89], v[50:65]
	s_cbranch_scc0 .LBB0_892
	s_lshl_b32 s1, s68, 2
	s_add_i32 s4, s1, 0
	s_and_b32 s0, s0, 1
	s_add_i32 s4, s4, 0x1e000
	s_mul_i32 s1, s0, 0x6000
	v_add_u32_e32 v70, s1, v179
	v_add_u32_e32 v71, v70, v178
	ds_read_b128 v[66:69], v71 offset:32768
	v_add_u32_e32 v153, v70, v180
	v_add_u32_e32 v155, v70, v181
	v_add_u32_e32 v157, v70, v182
	v_add_u32_e32 v159, v70, v183
	v_add_u32_e32 v160, v70, v184
	v_add_u32_e32 v161, v70, v185
	v_add_u32_e32 v162, v70, v186
	v_add_u32_e32 v163, v70, v187
	s_waitcnt lgkmcnt(0)
	v_mfma_f32_32x32x16_bf16 v[82:97], v[66:69], v[142:145], 0
	ds_read_b128 v[66:69], v153 offset:32768
	v_add_u32_e32 v170, v70, v188
	v_add_u32_e32 v171, v70, v189
	v_add_u32_e32 v172, v70, v190
	s_waitcnt lgkmcnt(0)
	v_mfma_f32_32x32x16_bf16 v[82:97], v[66:69], v[138:141], v[82:97]
	ds_read_b128 v[66:69], v155 offset:32768
	s_waitcnt lgkmcnt(0)
	v_mfma_f32_32x32x16_bf16 v[82:97], v[66:69], v[134:137], v[82:97]
	ds_read_b128 v[66:69], v157 offset:32768
	s_waitcnt lgkmcnt(0)
	v_mfma_f32_32x32x16_bf16 v[82:97], v[66:69], v[130:133], v[82:97]
	ds_read_b128 v[66:69], v159 offset:32768
	s_waitcnt lgkmcnt(0)
	v_mfma_f32_32x32x16_bf16 v[82:97], v[66:69], v[126:129], v[82:97]
	ds_read_b128 v[66:69], v160 offset:32768
	s_waitcnt lgkmcnt(0)
	v_mfma_f32_32x32x16_bf16 v[82:97], v[66:69], v[122:125], v[82:97]
	ds_read_b128 v[66:69], v161 offset:32768
	s_waitcnt lgkmcnt(0)
	v_mfma_f32_32x32x16_bf16 v[82:97], v[66:69], v[118:121], v[82:97]
	ds_read_b128 v[66:69], v162 offset:32768
	s_waitcnt lgkmcnt(0)
	v_mfma_f32_32x32x16_bf16 v[82:97], v[66:69], v[114:117], v[82:97]
	ds_read_b128 v[66:69], v163 offset:32768
	s_waitcnt lgkmcnt(0)
	v_mfma_f32_32x32x16_bf16 v[82:97], v[66:69], v[110:113], v[82:97]
	ds_read_b128 v[66:69], v170 offset:32768
	s_waitcnt lgkmcnt(0)
	v_mfma_f32_32x32x16_bf16 v[82:97], v[66:69], v[106:109], v[82:97]
	ds_read_b128 v[66:69], v171 offset:32768
	s_waitcnt lgkmcnt(0)
	v_mfma_f32_32x32x16_bf16 v[82:97], v[66:69], v[102:105], v[82:97]
	ds_read_b128 v[66:69], v172 offset:32768
	s_waitcnt lgkmcnt(0)
	v_mfma_f32_32x32x16_bf16 v[82:97], v[66:69], v[98:101], v[82:97]
	ds_read_b128 v[66:69], v71 offset:45056
	s_waitcnt lgkmcnt(0)
	v_mfma_f32_32x32x16_bf16 v[66:81], v[66:69], v[142:145], 0
	ds_read_b128 v[142:145], v153 offset:45056
	s_waitcnt lgkmcnt(0)
	v_mfma_f32_32x32x16_bf16 v[66:81], v[142:145], v[138:141], v[66:81]
	ds_read_b128 v[138:141], v155 offset:45056
	s_waitcnt lgkmcnt(0)
	v_mfma_f32_32x32x16_bf16 v[66:81], v[138:141], v[134:137], v[66:81]
	ds_read_b128 v[134:137], v157 offset:45056
	s_waitcnt lgkmcnt(0)
	v_mfma_f32_32x32x16_bf16 v[66:81], v[134:137], v[130:133], v[66:81]
	ds_read_b128 v[130:133], v159 offset:45056
	s_waitcnt lgkmcnt(0)
	v_mfma_f32_32x32x16_bf16 v[66:81], v[130:133], v[126:129], v[66:81]
	ds_read_b128 v[126:129], v160 offset:45056
	s_waitcnt lgkmcnt(0)
	v_mfma_f32_32x32x16_bf16 v[66:81], v[126:129], v[122:125], v[66:81]
	ds_read_b128 v[122:125], v161 offset:45056
	s_waitcnt lgkmcnt(0)
	v_mfma_f32_32x32x16_bf16 v[66:81], v[122:125], v[118:121], v[66:81]
	ds_read_b128 v[118:121], v162 offset:45056
	v_exp_f32_e32 v122, v97
	s_waitcnt lgkmcnt(0)
	v_mfma_f32_32x32x16_bf16 v[66:81], v[118:121], v[114:117], v[66:81]
	ds_read_b128 v[114:117], v163 offset:45056
	v_exp_f32_e32 v118, v93
	v_exp_f32_e32 v119, v94
	v_exp_f32_e32 v120, v95
	v_exp_f32_e32 v121, v96
	s_waitcnt lgkmcnt(0)
	v_mfma_f32_32x32x16_bf16 v[66:81], v[114:117], v[110:113], v[66:81]
	ds_read_b128 v[110:113], v170 offset:45056
	v_exp_f32_e32 v114, v89
	v_exp_f32_e32 v115, v90
	v_exp_f32_e32 v116, v91
	v_exp_f32_e32 v117, v92
	v_cvt_pk_bf16_f32 v89, v121, v122
	s_waitcnt lgkmcnt(0)
	v_mfma_f32_32x32x16_bf16 v[66:81], v[110:113], v[106:109], v[66:81]
	ds_read_b128 v[106:109], v171 offset:45056
	v_exp_f32_e32 v110, v85
	v_exp_f32_e32 v111, v86
	v_exp_f32_e32 v112, v87
	v_exp_f32_e32 v113, v88
	v_cvt_pk_bf16_f32 v86, v115, v116
	v_cvt_pk_bf16_f32 v87, v117, v118
	s_waitcnt lgkmcnt(0)
	v_mfma_f32_32x32x16_bf16 v[66:81], v[106:109], v[102:105], v[66:81]
	ds_read_b128 v[102:105], v172 offset:45056
	v_exp_f32_e32 v107, v82
	v_exp_f32_e32 v108, v83
	v_exp_f32_e32 v109, v84
	v_cvt_pk_bf16_f32 v84, v111, v112
	v_cvt_pk_bf16_f32 v85, v113, v114
	v_cvt_pk_bf16_f32 v82, v107, v108
	s_waitcnt lgkmcnt(0)
	v_mfma_f32_32x32x16_bf16 v[66:81], v[102:105], v[98:101], v[66:81]
	v_cvt_pk_bf16_f32 v83, v109, v110
	v_cvt_pk_bf16_f32 v88, v119, v120
	v_lshl_add_u32 v106, s0, 14, v176
	ds_read_b64_tr_b16 v[90:91], v106 offset:0
	ds_read_b64_tr_b16 v[92:93], v106 offset:0x800
	ds_read_b64_tr_b16 v[94:95], v106 offset:0x1000
	ds_read_b64_tr_b16 v[96:97], v106 offset:0x1800
	ds_read_b64_tr_b16 v[98:99], v106 offset:0x200
	ds_read_b64_tr_b16 v[100:101], v106 offset:0xa00
	ds_read_b64_tr_b16 v[102:103], v106 offset:0x1200
	ds_read_b64_tr_b16 v[104:105], v106 offset:0x1a00
	s_waitcnt lgkmcnt(4)
	s_nop 0
	v_mfma_f32_32x32x16_bf16 v[2:17], v[82:85], v[90:93], v[2:17]
	s_nop 2
	v_exp_f32_e32 v123, v66
	v_exp_f32_e32 v124, v67
	v_exp_f32_e32 v125, v68
	v_exp_f32_e32 v126, v69
	v_mfma_f32_32x32x16_bf16 v[2:17], v[86:89], v[94:97], v[2:17]
	ds_read_b64_tr_b16 v[66:67], v106 offset:0x400
	ds_read_b64_tr_b16 v[68:69], v106 offset:0xc00
	ds_read_b64_tr_b16 v[90:91], v106 offset:0x1400
	ds_read_b64_tr_b16 v[92:93], v106 offset:0x1c00
	s_waitcnt lgkmcnt(4)
	v_mfma_f32_32x32x16_bf16 v[18:33], v[82:85], v[98:101], v[18:33]
	v_exp_f32_e32 v98, v70
	v_exp_f32_e32 v99, v71
	v_exp_f32_e32 v100, v72
	v_exp_f32_e32 v101, v73
	v_mfma_f32_32x32x16_bf16 v[18:33], v[86:89], v[102:105], v[18:33]
	ds_read_b64_tr_b16 v[70:71], v106 offset:0x600
	ds_read_b64_tr_b16 v[72:73], v106 offset:0xe00
	ds_read_b64_tr_b16 v[94:95], v106 offset:0x1600
	ds_read_b64_tr_b16 v[96:97], v106 offset:0x1e00
	s_waitcnt lgkmcnt(4)
	v_mfma_f32_32x32x16_bf16 v[34:49], v[82:85], v[66:69], v[34:49]
	v_exp_f32_e32 v102, v74
	v_exp_f32_e32 v103, v75
	v_exp_f32_e32 v104, v76
	v_exp_f32_e32 v105, v77
	v_mfma_f32_32x32x16_bf16 v[34:49], v[86:89], v[90:93], v[34:49]
	ds_read_b64_tr_b16 v[74:75], v106 offset:0x2000
	ds_read_b64_tr_b16 v[76:77], v106 offset:0x2800
	ds_read_b64_tr_b16 v[90:91], v106 offset:0x3000
	ds_read_b64_tr_b16 v[92:93], v106 offset:0x3800
	s_waitcnt lgkmcnt(4)
	v_add_f32_e32 v66, v107, v108
	v_add_f32_e32 v67, v123, v124
	v_mfma_f32_32x32x16_bf16 v[50:65], v[82:85], v[70:73], v[50:65]
	v_add_f32_e32 v66, v66, v109
	v_add_f32_e32 v67, v67, v125
	v_exp_f32_e32 v127, v78
	v_add_f32_e32 v66, v66, v110
	v_add_f32_e32 v67, v67, v126
	v_exp_f32_e32 v128, v79
	v_add_f32_e32 v66, v66, v111
	v_add_f32_e32 v67, v67, v98
	v_mfma_f32_32x32x16_bf16 v[50:65], v[86:89], v[94:97], v[50:65]
	v_add_f32_e32 v66, v66, v112
	v_add_f32_e32 v67, v67, v99
	v_exp_f32_e32 v129, v80
	v_add_f32_e32 v66, v66, v113
	v_add_f32_e32 v67, v67, v100
	v_exp_f32_e32 v81, v81
	v_add_f32_e32 v66, v66, v114
	v_add_f32_e32 v67, v67, v101
	v_cvt_pk_bf16_f32 v68, v123, v124
	v_add_f32_e32 v66, v66, v115
	v_add_f32_e32 v67, v67, v102
	v_cvt_pk_bf16_f32 v69, v125, v126
	v_add_f32_e32 v66, v66, v116
	v_add_f32_e32 v67, v67, v103
	v_cvt_pk_bf16_f32 v70, v98, v99
	v_add_f32_e32 v66, v66, v117
	v_add_f32_e32 v67, v67, v104
	v_cvt_pk_bf16_f32 v71, v100, v101
	v_add_f32_e32 v66, v66, v118
	v_add_f32_e32 v67, v67, v105
	v_cvt_pk_bf16_f32 v78, v102, v103
	v_add_f32_e32 v66, v66, v119
	v_add_f32_e32 v67, v67, v127
	v_cvt_pk_bf16_f32 v79, v104, v105
	v_add_f32_e32 v66, v66, v120
	v_add_f32_e32 v67, v67, v128
	v_cvt_pk_bf16_f32 v80, v127, v128
	v_add_f32_e32 v66, v66, v121
	v_add_f32_e32 v67, v67, v129
	v_add_f32_e32 v66, v66, v122
	v_add_f32_e32 v67, v67, v81
	v_cvt_pk_bf16_f32 v81, v129, v81
	v_add_f32_e32 v66, v66, v67
	v_add_f32_e32 v66, v151, v66
	v_mov_b32_e32 v67, v66
	s_nop 1
	v_permlane32_swap_b32_e32 v66, v67
	ds_read_b64_tr_b16 v[82:83], v106 offset:0x2200
	ds_read_b64_tr_b16 v[84:85], v106 offset:0x2a00
	ds_read_b64_tr_b16 v[86:87], v106 offset:0x3200
	ds_read_b64_tr_b16 v[88:89], v106 offset:0x3a00
	s_waitcnt lgkmcnt(4)
	v_mfma_f32_32x32x16_bf16 v[2:17], v[68:71], v[74:77], v[2:17]
	s_nop 0
	v_mfma_f32_32x32x16_bf16 v[2:17], v[78:81], v[90:93], v[2:17]
	ds_read_b64_tr_b16 v[72:73], v106 offset:0x2400
	ds_read_b64_tr_b16 v[74:75], v106 offset:0x2c00
	ds_read_b64_tr_b16 v[90:91], v106 offset:0x3400
	ds_read_b64_tr_b16 v[92:93], v106 offset:0x3c00
	s_waitcnt lgkmcnt(4)
	v_mfma_f32_32x32x16_bf16 v[18:33], v[68:71], v[82:85], v[18:33]
	v_mfma_f32_32x32x16_bf16 v[18:33], v[78:81], v[86:89], v[18:33]
	ds_read_b64_tr_b16 v[82:83], v106 offset:0x2600
	ds_read_b64_tr_b16 v[84:85], v106 offset:0x2e00
	ds_read_b64_tr_b16 v[86:87], v106 offset:0x3600
	ds_read_b64_tr_b16 v[88:89], v106 offset:0x3e00
	s_waitcnt lgkmcnt(4)
	v_mfma_f32_32x32x16_bf16 v[34:49], v[68:71], v[72:75], v[34:49]
	v_mfma_f32_32x32x16_bf16 v[34:49], v[78:81], v[90:93], v[34:49]
	s_waitcnt lgkmcnt(0)
	v_mfma_f32_32x32x16_bf16 v[50:65], v[68:71], v[82:85], v[50:65]
	s_waitcnt vmcnt(0)
	s_barrier
	v_mfma_f32_32x32x16_bf16 v[50:65], v[78:81], v[86:89], v[50:65]
	s_and_saveexec_b64 s[0:1], s[2:3]
	s_cbranch_execz .LBB0_886
	v_add_f32_e32 v66, v66, v67
	v_lshl_add_u32 v68, v1, 2, s4
	ds_write_b32 v68, v66
	s_branch .LBB0_886

.LBB0_2311:
	s_ashr_i32 s14, s33, 9
	s_ashr_i32 s15, s14, 31
	s_lshl_b32 s0, s33, 8
	s_lshl_b64 s[8:9], s[14:15], 14
	s_and_b32 s0, s0, 0x3f00
	s_or_b32 s8, s8, s0
	s_lshl_b32 s0, s14, 8
	s_add_i32 s0, s0, 0x8000
	s_mul_i32 s4, s9, 0xc00
	s_mul_hi_u32 s12, s8, 0xc00
	s_bfe_u32 s36, s33, 0x30006
	s_ashr_i32 s1, s0, 31
	s_add_i32 s12, s12, s4
	s_mul_i32 s4, s8, 0xc00
	v_readlane_b32 s28, v242, 21
	v_readlane_b32 s29, v242, 22
	s_add_u32 s4, s28, s4
	s_addc_u32 s12, s29, s12
	s_mul_i32 s21, s36, 0x180
	s_add_u32 s28, s4, s21
	s_addc_u32 s29, s12, 0
	s_mul_i32 s12, s0, 0xc00
	s_mul_hi_i32 s4, s0, 0xc00
	s_add_u32 s12, s24, s12
	s_addc_u32 s4, s25, s4
	s_add_u32 s12, s12, s21
	s_addc_u32 s13, s4, 0
	s_mul_i32 s35, s14, 0x3000000
	s_mul_hi_i32 s4, s14, 0x3000000
	s_add_u32 s35, s24, s35
	s_addc_u32 s4, s25, s4
	s_add_u32 s38, s35, s21
	s_addc_u32 s39, s4, 0
	s_lshl_b64 s[0:1], s[0:1], 12
	s_add_u32 s0, s31, s0
	s_addc_u32 s1, s34, s1
	s_lshl_b32 s4, s36, 9
	s_add_u32 s0, s0, s4
	s_addc_u32 s1, s1, 0
	s_add_u32 s44, s0, 0x100
	s_addc_u32 s45, s1, 0
	s_lshl_b64 s[14:15], s[14:15], 26
	s_add_u32 s14, s31, s14
	s_addc_u32 s15, s34, s15
	s_add_u32 s4, s14, s4
	s_addc_u32 s14, s15, 0
	s_add_u32 s46, s4, 0x100
	v_readfirstlane_b32 s52, v0
	s_addc_u32 s47, s14, 0
	s_lshr_b32 s37, s52, 6
	s_lshl_b32 s35, s37, 5
	v_or_b32_e32 v4, s35, v165
	v_mov_b64_e32 v[2:3], s[28:29]
	v_mad_u64_u32 v[2:3], s[14:15], v4, s19, v[2:3]
	s_andn2_b32 s52, s52, 63
	v_lshl_add_u64 v[2:3], v[2:3], 0, v[148:149]
	global_load_dwordx4 v[142:145], v[2:3], off
	global_load_dwordx4 v[138:141], v[2:3], off offset:32
	global_load_dwordx4 v[134:137], v[2:3], off offset:64
	global_load_dwordx4 v[130:133], v[2:3], off offset:96
	global_load_dwordx4 v[126:129], v[2:3], off offset:128
	global_load_dwordx4 v[122:125], v[2:3], off offset:160
	global_load_dwordx4 v[118:121], v[2:3], off offset:192
	global_load_dwordx4 v[114:117], v[2:3], off offset:224
	global_load_dwordx4 v[110:113], v[2:3], off offset:256
	global_load_dwordx4 v[106:109], v[2:3], off offset:288
	global_load_dwordx4 v[102:105], v[2:3], off offset:320
	global_load_dwordx4 v[98:101], v[2:3], off offset:352
	v_or_b32_e32 v2, s52, v166
	v_mul_hi_i32 v3, v2, s20
	v_lshrrev_b32_e32 v4, 31, v3
	v_ashrrev_i32_e32 v3, 2, v3
	v_add_u32_e32 v3, v3, v4
	v_mul_lo_u32 v4, v3, 24
	v_sub_u32_e32 v4, v2, v4
	v_mul_lo_u32 v5, v3, s22
	v_lshrrev_b32_e32 v3, 1, v3
	v_bitop3_b32 v3, v3, v4, 7 bitop3:0x6c
	v_lshl_add_u32 v160, v3, 3, v5
	v_add_u32_e32 v3, 0x200, v2
	v_mul_hi_i32 v4, v3, s20
	v_lshrrev_b32_e32 v5, 31, v4
	v_ashrrev_i32_e32 v4, 2, v4
	v_add_u32_e32 v4, v4, v5
	v_mul_lo_u32 v5, v4, 24
	v_sub_u32_e32 v3, v3, v5
	v_mul_lo_u32 v5, v4, s22
	v_lshrrev_b32_e32 v4, 1, v4
	v_bitop3_b32 v3, v4, v3, 7 bitop3:0x6c
	v_lshl_add_u32 v162, v3, 3, v5
	v_add_u32_e32 v3, 0x400, v2
	v_mul_hi_i32 v4, v3, s20
	v_lshrrev_b32_e32 v5, 31, v4
	v_ashrrev_i32_e32 v4, 2, v4
	v_add_u32_e32 v4, v4, v5
	s_ashr_i32 s4, s52, 4
	v_mul_lo_u32 v5, v4, 24
	s_and_b32 s14, s4, 0x1ffff0
	s_lshr_b32 s4, s4, 1
	v_sub_u32_e32 v3, v3, v5
	v_mul_lo_u32 v5, v4, s22
	v_lshrrev_b32_e32 v4, 1, v4
	s_and_b32 s4, s4, 4
	v_bitop3_b32 v3, v4, v3, 7 bitop3:0x6c
	s_or_b32 s4, s14, s4
	v_lshl_add_u32 v168, v3, 3, v5
	v_or_b32_e32 v3, s4, v178
	v_lshrrev_b32_e32 v171, 1, v3
	v_xor_b32_e32 v171, v171, v3
	v_and_b32_e32 v171, 4, v171
	v_lshl_or_b32 v171, v171, 1, v171
	v_xor_b32_e32 v3, v3, v171
	s_add_i32 s4, s52, 0x200
	s_ashr_i32 s4, s4, 4
	s_and_b32 s14, s4, 0x1ffff0
	s_lshr_b32 s4, s4, 1
	s_and_b32 s4, s4, 4
	v_and_or_b32 v2, v2, s16, v177
	s_or_b32 s4, s14, s4
	v_lshl_or_b32 v170, v3, 11, v2
	v_or_b32_e32 v3, s4, v178
	v_lshrrev_b32_e32 v173, 1, v3
	v_xor_b32_e32 v173, v173, v3
	v_and_b32_e32 v173, 4, v173
	v_lshl_or_b32 v173, v173, 1, v173
	v_xor_b32_e32 v3, v3, v173
	s_lshl_b32 s4, s37, 10
	s_add_i32 s53, s4, 0
	v_ashrrev_i32_e32 v161, 31, v160
	v_lshl_or_b32 v172, v3, 11, v2
	s_add_i32 m0, s53, 0x8000
	v_lshl_add_u64 v[2:3], v[160:161], 1, s[12:13]
	v_ashrrev_i32_e32 v163, 31, v162
	global_load_lds_dwordx4 v[2:3], off
	v_lshl_add_u64 v[2:3], v[162:163], 1, s[12:13]
	s_add_i32 m0, s53, 0xa000
	v_ashrrev_i32_e32 v169, 31, v168
	global_load_lds_dwordx4 v[2:3], off
	v_lshl_add_u64 v[2:3], v[168:169], 1, s[12:13]
	s_add_i32 m0, s53, 0xc000
	v_ashrrev_i32_e32 v171, 31, v170
	global_load_lds_dwordx4 v[2:3], off
	v_lshl_add_u64 v[2:3], v[170:171], 1, s[0:1]
	v_lshl_add_u64 v[2:3], v[2:3], 0, s[6:7]
	s_mov_b32 m0, s53
	v_ashrrev_i32_e32 v173, 31, v172
	global_load_lds_dwordx4 v[2:3], off
	v_lshl_add_u64 v[2:3], v[172:173], 1, s[0:1]
	v_lshl_add_u64 v[2:3], v[2:3], 0, s[6:7]
	s_add_i32 m0, s53, 0x2000
	s_mov_b32 s4, -3
	global_load_lds_dwordx4 v[2:3], off
	s_waitcnt vmcnt(0)
	s_mov_b64 s[0:1], 64
	v_mov_b32_e32 v151, 0
	v_mov_b32_e32 v2, 0
	v_mov_b32_e32 v3, v147
	v_mov_b32_e32 v4, v147
	v_mov_b32_e32 v5, v147
	v_mov_b32_e32 v6, v147
	v_mov_b32_e32 v7, v147
	v_mov_b32_e32 v8, v147
	v_mov_b32_e32 v9, v147
	v_mov_b32_e32 v10, v147
	v_mov_b32_e32 v11, v147
	v_mov_b32_e32 v12, v147
	v_mov_b32_e32 v13, v147
	v_mov_b32_e32 v14, v147
	v_mov_b32_e32 v15, v147
	v_mov_b32_e32 v16, v147
	v_mov_b32_e32 v17, v147
	v_mov_b32_e32 v18, 0
	v_mov_b32_e32 v19, v147
	v_mov_b32_e32 v20, v147
	v_mov_b32_e32 v21, v147
	v_mov_b32_e32 v22, v147
	v_mov_b32_e32 v23, v147
	v_mov_b32_e32 v24, v147
	v_mov_b32_e32 v25, v147
	v_mov_b32_e32 v26, v147
	v_mov_b32_e32 v27, v147
	v_mov_b32_e32 v28, v147
	v_mov_b32_e32 v29, v147
	v_mov_b32_e32 v30, v147
	v_mov_b32_e32 v31, v147
	v_mov_b32_e32 v32, v147
	v_mov_b32_e32 v33, v147
	v_mov_b32_e32 v34, 0
	v_mov_b32_e32 v35, v147
	v_mov_b32_e32 v36, v147
	v_mov_b32_e32 v37, v147
	v_mov_b32_e32 v38, v147
	v_mov_b32_e32 v39, v147
	v_mov_b32_e32 v40, v147
	v_mov_b32_e32 v41, v147
	v_mov_b32_e32 v42, v147
	v_mov_b32_e32 v43, v147
	v_mov_b32_e32 v44, v147
	v_mov_b32_e32 v45, v147
	v_mov_b32_e32 v46, v147
	v_mov_b32_e32 v47, v147
	v_mov_b32_e32 v48, v147
	v_mov_b32_e32 v49, v147
	v_mov_b32_e32 v50, 0
	v_mov_b32_e32 v51, v147
	v_mov_b32_e32 v52, v147
	v_mov_b32_e32 v53, v147
	v_mov_b32_e32 v54, v147
	v_mov_b32_e32 v55, v147
	v_mov_b32_e32 v56, v147
	v_mov_b32_e32 v57, v147
	v_mov_b32_e32 v58, v147
	v_mov_b32_e32 v59, v147
	v_mov_b32_e32 v60, v147
	v_mov_b32_e32 v61, v147
	v_mov_b32_e32 v62, v147
	v_mov_b32_e32 v63, v147
	v_mov_b32_e32 v64, v147
	v_mov_b32_e32 v65, v147
	s_waitcnt vmcnt(0) lgkmcnt(0)
	s_barrier
	v_lshlrev_b32_e32 v238, 1, v160
	v_lshlrev_b32_e32 v239, 1, v162
	v_lshlrev_b32_e32 v240, 1, v168
	v_lshlrev_b32_e32 v241, 1, v170
	v_lshlrev_b32_e32 v244, 1, v172
.LBB0_2312:
	v_add_co_u32_e64 v66, s[14:15], s4, 3
	s_nop 0
	v_readfirstlane_b32 s21, v66
	s_and_b32 s21, s21, 1
	s_lshl_b64 s[28:29], s[4:5], 6
	s_and_b64 s[40:41], s[14:15], exec
	s_cselect_b32 s29, s1, s29
	s_cselect_b32 s28, s0, s28
	s_mul_i32 s42, s29, 0xc00
	s_mul_hi_u32 s43, s28, 0xc00
	s_cselect_b32 s41, s13, s39
	s_cselect_b32 s40, s12, s38
	s_add_i32 s43, s43, s42
	s_mul_i32 s42, s28, 0xc00
	s_add_u32 s40, s40, s42
	s_addc_u32 s41, s41, s43
	s_xor_b32 s42, s21, 1
	s_mulk_i32 s42, 0x6000
	s_add_i32 s42, s53, s42
	s_add_i32 m0, s42, 0x8000
	s_nop 0
	global_load_lds_dwordx4 v238, s[40:41]
	s_add_i32 m0, s42, 0xa000
	s_lshl_b64 s[28:29], s[28:29], 12
	global_load_lds_dwordx4 v239, s[40:41]
	s_add_i32 m0, s42, 0xc000
	s_and_b64 s[14:15], s[14:15], exec
	s_cselect_b32 s14, s44, s46
	s_cselect_b32 s15, s45, s47
	s_add_u32 s14, s14, s28
	s_addc_u32 s15, s15, s29
	s_lshl_b32 s28, s21, 14
	s_xor_b32 s29, s28, 0x4000
	s_add_i32 s29, s53, s29
	global_load_lds_dwordx4 v240, s[40:41]
	s_mov_b32 m0, s29
	s_mulk_i32 s21, 0x6000
	global_load_lds_dwordx4 v241, s[14:15]
	s_add_i32 m0, s29, 0x2000
	s_nop 0
	global_load_lds_dwordx4 v244, s[14:15]
	v_add_u32_e32 v74, s21, v182
	v_add_u32_e32 v75, v74, v181
	ds_read_b128 v[66:69], v75 offset:32768
	v_add_u32_e32 v76, v74, v183
	ds_read_b128 v[70:73], v76 offset:32768
	v_add_u32_e32 v153, v74, v184
	v_add_u32_e32 v155, v74, v185
	v_add_u32_e32 v157, v74, v186
	v_add_u32_e32 v159, v74, v187
	v_add_u32_e32 v209, v74, v188
	v_add_u32_e32 v218, v74, v189
	s_waitcnt lgkmcnt(0)
	v_mfma_f32_32x32x16_bf16 v[82:97], v[66:69], v[142:145], 0
	ds_read_b128 v[66:69], v153 offset:32768
	v_add_u32_e32 v219, v74, v190
	v_add_u32_e32 v220, v74, v191
	v_add_u32_e32 v221, v74, v192
	v_add_u32_e32 v222, v74, v193
	v_mfma_f32_32x32x16_bf16 v[82:97], v[70:73], v[138:141], v[82:97]
	ds_read_b128 v[70:73], v155 offset:32768
	s_waitcnt lgkmcnt(0)
	v_mfma_f32_32x32x16_bf16 v[82:97], v[66:69], v[134:137], v[82:97]
	ds_read_b128 v[66:69], v157 offset:32768
	v_mfma_f32_32x32x16_bf16 v[82:97], v[70:73], v[130:133], v[82:97]
	ds_read_b128 v[70:73], v159 offset:32768
	s_waitcnt lgkmcnt(0)
	v_mfma_f32_32x32x16_bf16 v[82:97], v[66:69], v[126:129], v[82:97]
	ds_read_b128 v[66:69], v209 offset:32768
	v_mfma_f32_32x32x16_bf16 v[82:97], v[70:73], v[122:125], v[82:97]
	ds_read_b128 v[70:73], v218 offset:32768
	s_waitcnt lgkmcnt(0)
	v_mfma_f32_32x32x16_bf16 v[82:97], v[66:69], v[118:121], v[82:97]
	ds_read_b128 v[66:69], v219 offset:32768
	v_mfma_f32_32x32x16_bf16 v[82:97], v[70:73], v[114:117], v[82:97]
	ds_read_b128 v[70:73], v220 offset:32768
	s_waitcnt lgkmcnt(0)
	v_mfma_f32_32x32x16_bf16 v[82:97], v[66:69], v[110:113], v[82:97]
	ds_read_b128 v[66:69], v221 offset:32768
	v_mfma_f32_32x32x16_bf16 v[82:97], v[70:73], v[106:109], v[82:97]
	ds_read_b128 v[70:73], v222 offset:32768
	s_waitcnt lgkmcnt(0)
	v_mfma_f32_32x32x16_bf16 v[82:97], v[66:69], v[102:105], v[82:97]
	v_mfma_f32_32x32x16_bf16 v[82:97], v[70:73], v[98:101], v[82:97]
	ds_read_b128 v[66:69], v75 offset:45056
	ds_read_b128 v[210:213], v76 offset:45056
	s_nop 9
	v_exp_f32_e32 v226, v86
	v_exp_f32_e32 v227, v87
	v_exp_f32_e32 v228, v88
	s_waitcnt lgkmcnt(0)
	v_mfma_f32_32x32x16_bf16 v[66:81], v[66:69], v[142:145], 0
	v_exp_f32_e32 v229, v89
	v_exp_f32_e32 v230, v90
	v_exp_f32_e32 v231, v91
	v_exp_f32_e32 v232, v92
	v_exp_f32_e32 v233, v93
	v_exp_f32_e32 v234, v94
	v_exp_f32_e32 v235, v95
	v_mfma_f32_32x32x16_bf16 v[66:81], v[210:213], v[138:141], v[66:81]
	ds_read_b128 v[210:213], v153 offset:45056
	ds_read_b128 v[214:217], v155 offset:45056
	v_exp_f32_e32 v155, v82
	v_exp_f32_e32 v236, v96
	v_exp_f32_e32 v237, v97
	v_cvt_pk_bf16_f32 v86, v230, v231
	v_cvt_pk_bf16_f32 v87, v232, v233
	v_cvt_pk_bf16_f32 v88, v234, v235
	s_waitcnt lgkmcnt(0)
	v_mfma_f32_32x32x16_bf16 v[66:81], v[210:213], v[134:137], v[66:81]
	v_cvt_pk_bf16_f32 v89, v236, v237
	v_add_u32_e32 v153, s28, v179
	v_mfma_f32_32x32x16_bf16 v[66:81], v[214:217], v[130:133], v[66:81]
	ds_read_b128 v[210:213], v157 offset:45056
	ds_read_b128 v[214:217], v159 offset:45056
	v_exp_f32_e32 v157, v83
	v_exp_f32_e32 v159, v84
	v_cvt_pk_bf16_f32 v84, v226, v227
	v_cvt_pk_bf16_f32 v82, v155, v157
	s_nop 1
	s_waitcnt lgkmcnt(0)
	v_mfma_f32_32x32x16_bf16 v[66:81], v[210:213], v[126:129], v[66:81]
	v_mfma_f32_32x32x16_bf16 v[66:81], v[214:217], v[122:125], v[66:81]
	ds_read_b128 v[210:213], v209 offset:45056
	ds_read_b128 v[214:217], v218 offset:45056
	v_exp_f32_e32 v209, v85
	v_cvt_pk_bf16_f32 v85, v228, v229
	v_cvt_pk_bf16_f32 v83, v159, v209
	s_nop 1
	s_waitcnt lgkmcnt(0)
	v_mfma_f32_32x32x16_bf16 v[66:81], v[210:213], v[118:121], v[66:81]
	ds_read_b128 v[210:213], v219 offset:45056
	v_mfma_f32_32x32x16_bf16 v[66:81], v[214:217], v[114:117], v[66:81]
	ds_read_b128 v[214:217], v220 offset:45056
	ds_read_b128 v[218:221], v221 offset:45056
	ds_read_b128 v[222:225], v222 offset:45056
	s_waitcnt lgkmcnt(0)
	v_mfma_f32_32x32x16_bf16 v[66:81], v[210:213], v[110:113], v[66:81]
	v_mfma_f32_32x32x16_bf16 v[66:81], v[214:217], v[106:109], v[66:81]
	v_mfma_f32_32x32x16_bf16 v[66:81], v[218:221], v[102:105], v[66:81]
	v_mfma_f32_32x32x16_bf16 v[66:81], v[222:225], v[98:101], v[66:81]
	ds_read_b64_tr_b16 v[90:91], v153 offset:0
	ds_read_b64_tr_b16 v[92:93], v153 offset:0x800
	ds_read_b64_tr_b16 v[94:95], v153 offset:0x1000
	ds_read_b64_tr_b16 v[96:97], v153 offset:0x1800
	ds_read_b64_tr_b16 v[210:211], v153 offset:0x200
	ds_read_b64_tr_b16 v[212:213], v153 offset:0xa00
	ds_read_b64_tr_b16 v[214:215], v153 offset:0x1200
	ds_read_b64_tr_b16 v[216:217], v153 offset:0x1a00
	s_waitcnt lgkmcnt(4)
	s_nop 0
	v_mfma_f32_32x32x16_bf16 v[2:17], v[82:85], v[90:93], v[2:17]
	s_nop 9
	v_exp_f32_e32 v218, v66
	v_exp_f32_e32 v219, v67
	v_exp_f32_e32 v220, v68
	v_exp_f32_e32 v221, v69
	v_mfma_f32_32x32x16_bf16 v[2:17], v[86:89], v[94:97], v[2:17]
	ds_read_b64_tr_b16 v[66:67], v153 offset:0x400
	ds_read_b64_tr_b16 v[68:69], v153 offset:0xc00
	ds_read_b64_tr_b16 v[90:91], v153 offset:0x1400
	ds_read_b64_tr_b16 v[92:93], v153 offset:0x1c00
	s_waitcnt lgkmcnt(4)
	v_mfma_f32_32x32x16_bf16 v[18:33], v[82:85], v[210:213], v[18:33]
	v_exp_f32_e32 v210, v70
	v_exp_f32_e32 v211, v71
	v_exp_f32_e32 v212, v72
	v_exp_f32_e32 v213, v73
	v_mfma_f32_32x32x16_bf16 v[18:33], v[86:89], v[214:217], v[18:33]
	ds_read_b64_tr_b16 v[70:71], v153 offset:0x600
	ds_read_b64_tr_b16 v[72:73], v153 offset:0xe00
	ds_read_b64_tr_b16 v[94:95], v153 offset:0x1600
	ds_read_b64_tr_b16 v[96:97], v153 offset:0x1e00
	s_waitcnt lgkmcnt(4)
	v_mfma_f32_32x32x16_bf16 v[34:49], v[82:85], v[66:69], v[34:49]
	v_exp_f32_e32 v214, v74
	v_exp_f32_e32 v215, v75
	v_exp_f32_e32 v216, v76
	v_exp_f32_e32 v217, v77
	v_mfma_f32_32x32x16_bf16 v[34:49], v[86:89], v[90:93], v[34:49]
	ds_read_b64_tr_b16 v[66:67], v153 offset:0x2000
	ds_read_b64_tr_b16 v[68:69], v153 offset:0x2800
	ds_read_b64_tr_b16 v[74:75], v153 offset:0x3000
	ds_read_b64_tr_b16 v[76:77], v153 offset:0x3800
	s_waitcnt lgkmcnt(4)
	v_exp_f32_e32 v90, v78
	v_mfma_f32_32x32x16_bf16 v[50:65], v[82:85], v[70:73], v[50:65]
	v_exp_f32_e32 v91, v79
	v_cvt_pk_bf16_f32 v72, v210, v211
	v_cvt_pk_bf16_f32 v73, v212, v213
	v_mfma_f32_32x32x16_bf16 v[50:65], v[86:89], v[94:97], v[50:65]
	v_exp_f32_e32 v92, v80
	v_exp_f32_e32 v248, v81
	v_cvt_pk_bf16_f32 v78, v214, v215
	v_cvt_pk_bf16_f32 v79, v216, v217
	v_cvt_pk_bf16_f32 v80, v90, v91
	v_cvt_pk_bf16_f32 v70, v218, v219
	v_cvt_pk_bf16_f32 v71, v220, v221
	v_cvt_pk_bf16_f32 v81, v92, v248
	s_nop 0
	ds_read_b64_tr_b16 v[82:83], v153 offset:0x2200
	ds_read_b64_tr_b16 v[84:85], v153 offset:0x2a00
	ds_read_b64_tr_b16 v[86:87], v153 offset:0x3200
	ds_read_b64_tr_b16 v[88:89], v153 offset:0x3a00
	s_waitcnt lgkmcnt(4)
	s_nop 0
	v_mfma_f32_32x32x16_bf16 v[2:17], v[70:73], v[66:69], v[2:17]
	v_add_f32_e32 v246, v155, v157
	v_add_f32_e32 v247, v218, v219
	v_add_f32_e32 v246, v246, v159
	v_add_f32_e32 v247, v247, v220
	v_mfma_f32_32x32x16_bf16 v[2:17], v[78:81], v[74:77], v[2:17]
	v_add_f32_e32 v246, v246, v209
	v_add_f32_e32 v247, v247, v221
	v_add_f32_e32 v246, v246, v226
	v_add_f32_e32 v247, v247, v210
	ds_read_b64_tr_b16 v[66:67], v153 offset:0x2400
	ds_read_b64_tr_b16 v[68:69], v153 offset:0x2c00
	ds_read_b64_tr_b16 v[74:75], v153 offset:0x3400
	ds_read_b64_tr_b16 v[76:77], v153 offset:0x3c00
	s_waitcnt lgkmcnt(4)
	v_mfma_f32_32x32x16_bf16 v[18:33], v[70:73], v[82:85], v[18:33]
	v_add_f32_e32 v246, v246, v227
	v_add_f32_e32 v247, v247, v211
	v_add_f32_e32 v246, v246, v228
	v_add_f32_e32 v247, v247, v212
	v_mfma_f32_32x32x16_bf16 v[18:33], v[78:81], v[86:89], v[18:33]
	v_add_f32_e32 v246, v246, v229
	v_add_f32_e32 v247, v247, v213
	v_add_f32_e32 v246, v246, v230
	v_add_f32_e32 v247, v247, v214
	ds_read_b64_tr_b16 v[82:83], v153 offset:0x2600
	ds_read_b64_tr_b16 v[84:85], v153 offset:0x2e00
	ds_read_b64_tr_b16 v[86:87], v153 offset:0x3600
	ds_read_b64_tr_b16 v[88:89], v153 offset:0x3e00
	s_waitcnt lgkmcnt(4)
	v_mfma_f32_32x32x16_bf16 v[34:49], v[70:73], v[66:69], v[34:49]
	v_add_f32_e32 v246, v246, v231
	v_add_f32_e32 v247, v247, v215
	v_add_f32_e32 v246, v246, v232
	v_add_f32_e32 v247, v247, v216
	v_mfma_f32_32x32x16_bf16 v[34:49], v[78:81], v[74:77], v[34:49]
	v_add_f32_e32 v246, v246, v233
	v_add_f32_e32 v247, v247, v217
	v_add_f32_e32 v246, v246, v234
	v_add_f32_e32 v247, v247, v90
	s_waitcnt lgkmcnt(0)
	v_mfma_f32_32x32x16_bf16 v[50:65], v[70:73], v[82:85], v[50:65]
	v_add_f32_e32 v246, v246, v235
	v_add_f32_e32 v247, v247, v91
	v_add_f32_e32 v246, v246, v236
	v_add_f32_e32 v247, v247, v92
	v_add_f32_e32 v246, v246, v237
	v_add_f32_e32 v247, v247, v248
	v_add_f32_e32 v246, v246, v247
	v_add_f32_e32 v151, v151, v246
	s_waitcnt vmcnt(0)
	s_add_u32 s0, s0, 64
	s_addc_u32 s1, s1, 0
	s_add_i32 s4, s4, 1
	s_cmpk_eq_i32 s0, 0x4100
	s_waitcnt vmcnt(0)
	s_barrier
	v_mfma_f32_32x32x16_bf16 v[50:65], v[78:81], v[86:89], v[50:65]
	s_cbranch_scc0 .LBB0_2312
	s_lshl_b32 s0, s52, 2
	s_add_i32 s4, s0, 0
	s_add_i32 s4, s4, 0x1e000
	ds_read_b128 v[66:69], v196
	ds_read_b128 v[70:73], v197
	s_waitcnt lgkmcnt(1)
	v_mfma_f32_32x32x16_bf16 v[82:97], v[66:69], v[142:145], 0
	s_waitcnt lgkmcnt(0)
	v_mfma_f32_32x32x16_bf16 v[82:97], v[70:73], v[138:141], v[82:97]
	ds_read_b128 v[66:69], v198
	ds_read_b128 v[70:73], v199
	s_waitcnt lgkmcnt(1)
	v_mfma_f32_32x32x16_bf16 v[82:97], v[66:69], v[134:137], v[82:97]
	s_waitcnt lgkmcnt(0)
	v_mfma_f32_32x32x16_bf16 v[82:97], v[70:73], v[130:133], v[82:97]
	ds_read_b128 v[66:69], v200
	ds_read_b128 v[70:73], v201
	s_waitcnt lgkmcnt(1)
	v_mfma_f32_32x32x16_bf16 v[82:97], v[66:69], v[126:129], v[82:97]
	s_waitcnt lgkmcnt(0)
	v_mfma_f32_32x32x16_bf16 v[82:97], v[70:73], v[122:125], v[82:97]
	ds_read_b128 v[66:69], v202
	ds_read_b128 v[70:73], v203
	s_waitcnt lgkmcnt(1)
	v_mfma_f32_32x32x16_bf16 v[82:97], v[66:69], v[118:121], v[82:97]
	s_waitcnt lgkmcnt(0)
	v_mfma_f32_32x32x16_bf16 v[82:97], v[70:73], v[114:117], v[82:97]
	ds_read_b128 v[66:69], v204
	ds_read_b128 v[70:73], v205
	s_waitcnt lgkmcnt(1)
	v_mfma_f32_32x32x16_bf16 v[82:97], v[66:69], v[110:113], v[82:97]
	s_waitcnt lgkmcnt(0)
	v_mfma_f32_32x32x16_bf16 v[82:97], v[70:73], v[106:109], v[82:97]
	ds_read_b128 v[66:69], v206
	ds_read_b128 v[70:73], v207
	s_waitcnt lgkmcnt(1)
	v_mfma_f32_32x32x16_bf16 v[82:97], v[66:69], v[102:105], v[82:97]
	s_waitcnt lgkmcnt(0)
	v_mfma_f32_32x32x16_bf16 v[82:97], v[70:73], v[98:101], v[82:97]
	ds_read_b128 v[66:69], v196 offset:12288
	ds_read_b128 v[160:163], v197 offset:12288
	s_waitcnt lgkmcnt(1)
	v_mfma_f32_32x32x16_bf16 v[66:81], v[66:69], v[142:145], 0
	s_waitcnt lgkmcnt(0)
	v_mfma_f32_32x32x16_bf16 v[66:81], v[160:163], v[138:141], v[66:81]
	ds_read_b128 v[138:141], v198 offset:12288
	ds_read_b128 v[142:145], v199 offset:12288
	s_waitcnt lgkmcnt(1)
	v_mfma_f32_32x32x16_bf16 v[66:81], v[138:141], v[134:137], v[66:81]
	s_waitcnt lgkmcnt(0)
	v_mfma_f32_32x32x16_bf16 v[66:81], v[142:145], v[130:133], v[66:81]
	ds_read_b128 v[130:133], v200 offset:12288
	ds_read_b128 v[134:137], v201 offset:12288
	s_waitcnt lgkmcnt(1)
	v_mfma_f32_32x32x16_bf16 v[66:81], v[130:133], v[126:129], v[66:81]
	v_exp_f32_e32 v130, v82
	v_exp_f32_e32 v131, v83
	v_exp_f32_e32 v132, v84
	v_cvt_pk_bf16_f32 v82, v130, v131
	s_waitcnt lgkmcnt(0)
	v_mfma_f32_32x32x16_bf16 v[66:81], v[134:137], v[122:125], v[66:81]
	ds_read_b128 v[122:125], v202 offset:12288
	ds_read_b128 v[126:129], v203 offset:12288
	s_waitcnt lgkmcnt(1)
	v_mfma_f32_32x32x16_bf16 v[66:81], v[122:125], v[118:121], v[66:81]
	s_waitcnt lgkmcnt(0)
	v_mfma_f32_32x32x16_bf16 v[66:81], v[126:129], v[114:117], v[66:81]
	ds_read_b128 v[114:117], v204 offset:12288
	ds_read_b128 v[118:121], v205 offset:12288
	ds_read_b128 v[122:125], v206 offset:12288
	ds_read_b128 v[126:129], v207 offset:12288
	s_waitcnt lgkmcnt(3)
	v_mfma_f32_32x32x16_bf16 v[66:81], v[114:117], v[110:113], v[66:81]
	v_exp_f32_e32 v110, v85
	v_exp_f32_e32 v111, v86
	v_exp_f32_e32 v112, v87
	v_exp_f32_e32 v113, v88
	v_exp_f32_e32 v114, v89
	v_exp_f32_e32 v115, v90
	v_exp_f32_e32 v116, v91
	s_waitcnt lgkmcnt(2)
	v_mfma_f32_32x32x16_bf16 v[66:81], v[118:121], v[106:109], v[66:81]
	v_exp_f32_e32 v106, v92
	v_exp_f32_e32 v107, v93
	v_exp_f32_e32 v108, v94
	v_exp_f32_e32 v109, v95
	v_exp_f32_e32 v117, v96
	v_exp_f32_e32 v118, v97
	v_cvt_pk_bf16_f32 v83, v132, v110
	s_waitcnt lgkmcnt(1)
	v_mfma_f32_32x32x16_bf16 v[66:81], v[122:125], v[102:105], v[66:81]
	v_cvt_pk_bf16_f32 v84, v111, v112
	v_cvt_pk_bf16_f32 v85, v113, v114
	v_cvt_pk_bf16_f32 v86, v115, v116
	v_cvt_pk_bf16_f32 v87, v106, v107
	v_cvt_pk_bf16_f32 v88, v108, v109
	v_cvt_pk_bf16_f32 v89, v117, v118
	s_waitcnt lgkmcnt(0)
	v_mfma_f32_32x32x16_bf16 v[66:81], v[126:129], v[98:101], v[66:81]
	ds_read_b64_tr_b16 v[90:91], v208 offset:0
	ds_read_b64_tr_b16 v[92:93], v208 offset:0x800
	ds_read_b64_tr_b16 v[94:95], v208 offset:0x1000
	ds_read_b64_tr_b16 v[96:97], v208 offset:0x1800
	ds_read_b64_tr_b16 v[98:99], v208 offset:0x200
	ds_read_b64_tr_b16 v[100:101], v208 offset:0xa00
	ds_read_b64_tr_b16 v[102:103], v208 offset:0x1200
	ds_read_b64_tr_b16 v[104:105], v208 offset:0x1a00
	s_waitcnt lgkmcnt(4)
	s_nop 0
	v_mfma_f32_32x32x16_bf16 v[2:17], v[82:85], v[90:93], v[2:17]
	s_nop 6
	v_exp_f32_e32 v119, v66
	v_exp_f32_e32 v120, v67
	v_exp_f32_e32 v121, v68
	v_exp_f32_e32 v122, v69
	v_mfma_f32_32x32x16_bf16 v[2:17], v[86:89], v[94:97], v[2:17]
	ds_read_b64_tr_b16 v[66:67], v208 offset:0x400
	ds_read_b64_tr_b16 v[68:69], v208 offset:0xc00
	ds_read_b64_tr_b16 v[90:91], v208 offset:0x1400
	ds_read_b64_tr_b16 v[92:93], v208 offset:0x1c00
	s_waitcnt lgkmcnt(4)
	v_mfma_f32_32x32x16_bf16 v[18:33], v[82:85], v[98:101], v[18:33]
	v_exp_f32_e32 v98, v70
	v_exp_f32_e32 v99, v71
	v_exp_f32_e32 v100, v72
	v_exp_f32_e32 v101, v73
	v_mfma_f32_32x32x16_bf16 v[18:33], v[86:89], v[102:105], v[18:33]
	ds_read_b64_tr_b16 v[70:71], v208 offset:0x600
	ds_read_b64_tr_b16 v[72:73], v208 offset:0xe00
	ds_read_b64_tr_b16 v[94:95], v208 offset:0x1600
	ds_read_b64_tr_b16 v[96:97], v208 offset:0x1e00
	s_waitcnt lgkmcnt(4)
	v_mfma_f32_32x32x16_bf16 v[34:49], v[82:85], v[66:69], v[34:49]
	v_exp_f32_e32 v102, v74
	v_exp_f32_e32 v103, v75
	v_exp_f32_e32 v104, v76
	v_exp_f32_e32 v105, v77
	v_mfma_f32_32x32x16_bf16 v[34:49], v[86:89], v[90:93], v[34:49]
	ds_read_b64_tr_b16 v[74:75], v208 offset:0x2000
	ds_read_b64_tr_b16 v[76:77], v208 offset:0x2800
	ds_read_b64_tr_b16 v[90:91], v208 offset:0x3000
	ds_read_b64_tr_b16 v[92:93], v208 offset:0x3800
	s_waitcnt lgkmcnt(4)
	v_add_f32_e32 v66, v130, v131
	v_add_f32_e32 v67, v119, v120
	v_mfma_f32_32x32x16_bf16 v[50:65], v[82:85], v[70:73], v[50:65]
	v_add_f32_e32 v66, v66, v132
	v_add_f32_e32 v67, v67, v121
	v_exp_f32_e32 v123, v78
	v_add_f32_e32 v66, v66, v110
	v_add_f32_e32 v67, v67, v122
	v_exp_f32_e32 v124, v79
	v_add_f32_e32 v66, v66, v111
	v_add_f32_e32 v67, v67, v98
	v_mfma_f32_32x32x16_bf16 v[50:65], v[86:89], v[94:97], v[50:65]
	v_add_f32_e32 v66, v66, v112
	v_add_f32_e32 v67, v67, v99
	v_exp_f32_e32 v125, v80
	v_add_f32_e32 v66, v66, v113
	v_add_f32_e32 v67, v67, v100
	v_exp_f32_e32 v81, v81
	v_add_f32_e32 v66, v66, v114
	v_add_f32_e32 v67, v67, v101
	v_cvt_pk_bf16_f32 v68, v119, v120
	v_add_f32_e32 v66, v66, v115
	v_add_f32_e32 v67, v67, v102
	v_cvt_pk_bf16_f32 v69, v121, v122
	v_add_f32_e32 v66, v66, v116
	v_add_f32_e32 v67, v67, v103
	v_cvt_pk_bf16_f32 v70, v98, v99
	v_add_f32_e32 v66, v66, v106
	v_add_f32_e32 v67, v67, v104
	v_cvt_pk_bf16_f32 v71, v100, v101
	v_add_f32_e32 v66, v66, v107
	v_add_f32_e32 v67, v67, v105
	v_cvt_pk_bf16_f32 v78, v102, v103
	v_add_f32_e32 v66, v66, v108
	v_add_f32_e32 v67, v67, v123
	v_cvt_pk_bf16_f32 v79, v104, v105
	v_add_f32_e32 v66, v66, v109
	v_add_f32_e32 v67, v67, v124
	v_cvt_pk_bf16_f32 v80, v123, v124
	v_add_f32_e32 v66, v66, v117
	v_add_f32_e32 v67, v67, v125
	v_add_f32_e32 v66, v66, v118
	v_add_f32_e32 v67, v67, v81
	v_cvt_pk_bf16_f32 v81, v125, v81
	v_add_f32_e32 v66, v66, v67
	v_add_f32_e32 v66, v151, v66
	v_mov_b32_e32 v67, v66
	s_nop 1
	v_permlane32_swap_b32_e32 v66, v67
	ds_read_b64_tr_b16 v[82:83], v208 offset:0x2200
	ds_read_b64_tr_b16 v[84:85], v208 offset:0x2a00
	ds_read_b64_tr_b16 v[86:87], v208 offset:0x3200
	ds_read_b64_tr_b16 v[88:89], v208 offset:0x3a00
	s_waitcnt lgkmcnt(4)
	v_mfma_f32_32x32x16_bf16 v[2:17], v[68:71], v[74:77], v[2:17]
	s_nop 0
	v_mfma_f32_32x32x16_bf16 v[2:17], v[78:81], v[90:93], v[2:17]
	ds_read_b64_tr_b16 v[72:73], v208 offset:0x2400
	ds_read_b64_tr_b16 v[74:75], v208 offset:0x2c00
	ds_read_b64_tr_b16 v[90:91], v208 offset:0x3400
	ds_read_b64_tr_b16 v[92:93], v208 offset:0x3c00
	s_waitcnt lgkmcnt(4)
	v_mfma_f32_32x32x16_bf16 v[18:33], v[68:71], v[82:85], v[18:33]
	v_mfma_f32_32x32x16_bf16 v[18:33], v[78:81], v[86:89], v[18:33]
	ds_read_b64_tr_b16 v[82:83], v208 offset:0x2600
	ds_read_b64_tr_b16 v[84:85], v208 offset:0x2e00
	ds_read_b64_tr_b16 v[86:87], v208 offset:0x3600
	ds_read_b64_tr_b16 v[88:89], v208 offset:0x3e00
	s_waitcnt lgkmcnt(4)
	v_mfma_f32_32x32x16_bf16 v[34:49], v[68:71], v[72:75], v[34:49]
	v_mfma_f32_32x32x16_bf16 v[34:49], v[78:81], v[90:93], v[34:49]
	s_waitcnt lgkmcnt(0)
	v_mfma_f32_32x32x16_bf16 v[50:65], v[68:71], v[82:85], v[50:65]
	s_waitcnt vmcnt(0)
	s_barrier
	v_mfma_f32_32x32x16_bf16 v[50:65], v[78:81], v[86:89], v[50:65]
	s_and_saveexec_b64 s[0:1], s[2:3]
	s_cbranch_execz .LBB0_2310
	v_add_f32_e32 v66, v66, v67
	v_lshl_add_u32 v68, v165, 2, s4
	ds_write_b32 v68, v66
	s_branch .LBB0_2310
